# P1: hand-written EpiZ fast path for q/k/v tiles too: rope table loads software-pipelined 3 groups ahead, permlane16_swap pairing instead of bpermute, wave-uniform kv stores
# baseline (speedup 1.0000x reference)
;     __device__ __forceinline__ void operator()(const f32x4 (&acc)[2][2][4][2], const Unit& u, int wr, int wc, int fr, int fq) const {
;         const int pn = u.pn;
;         const bool do_rope = (pn < 6) && ((wc & 1) == 0);
;         const bool is_kv = (pn >= 3 && pn < 9);
;         const int kvsel = is_kv ? (pn - 3) / 3 : 0;
;         const int g = is_kv ? (pn - 3) % 3 : 0;
;         const int W = 128 << (2 * g);
;         const size_t okp = g == 0 ? O_KV128_P : (g == 1 ? O_KV512_P : O_KV2048_P);
;         const size_t oks = g == 0 ? O_KV128_S : (g == 1 ? O_KV512_S : O_KV2048_S);
;         const bool is_conv = (pn >= 9 && pn < 17);
.LBB0_133:
	s_cmp_lt_i32 s48, 6
	v_readlane_b32 s12, v253, 27
	s_cselect_b64 s[10:11], -1, 0
	v_readlane_b32 s13, v253, 28
	s_lshl_b32 s14, s18, 8
	v_readlane_b32 s1, v253, 23
	s_and_b64 s[10:11], s[12:13], s[10:11]
	s_add_i32 s14, s14, s1
	v_or_b32_e32 v187, s14, v184
	s_cmp_gt_u32 s48, 16
	s_cbranch_scc1 .Lz_lean
	s_cmp_lt_u32 s48, 3
	s_cbranch_scc1 .Lz_fast
	s_cmp_eq_u32 s18, 64
	s_cbranch_scc1 .Lz_orig
	s_cmp_lt_u32 s48, 9
	s_cbranch_scc1 .Lz_fast
	s_and_b32 s98, s18, 15
	s_cmp_lt_u32 s98, 15
	s_cbranch_scc1 .Lz_lean

;     __device__ __forceinline__ void operator()(const f32x4 (&acc)[2][2][4][2], const Unit& u, int wr, int wc, int fr, int fq) const {
;     ...
;         const bool do_rope = (pn < 6) && ((wc & 1) == 0);
;         const bool is_kv = (pn >= 3 && pn < 9);
;         const int kvsel = is_kv ? (pn - 3) / 3 : 0;
;         const int g = is_kv ? (pn - 3) % 3 : 0;
;         const int W = 128 << (2 * g);
;         const size_t okp = g == 0 ? O_KV128_P : (g == 1 ? O_KV512_P : O_KV2048_P);
;         const size_t oks = g == 0 ? O_KV128_S : (g == 1 ? O_KV512_S : O_KV2048_S);
;         const bool is_conv = (pn >= 9 && pn < 17);
;         const float sgn = fq == 0 ? -1.f : 1.f;
; #pragma unroll
;         for (int ai = 0; ai < 2; ++ai)
; #pragma unroll
;             for (int m = 0; m < 4; ++m) {
;                 const int row = u.pm * BM + ai * HALF + wr * 64 + m * 16 + fr;
;                 const bool isP = row < MP, isS = (row >= MP) && (row < MT);
;                 const int b = isP ? (row >> 12) : (row - MP);
;                 const int t = row & 4095;
;                 float cosv[8], sinv[8];
;                 if (do_rope) {
;                     const f32x4* cs = (const f32x4*)(rope + (size_t)(isP ? t : 4096) * 16);
; #pragma unroll
;                     for (int q = 0; q < 4; ++q) { const f32x4 c = cs[q]; cosv[2 * q] = c[0]; sinv[2 * q] = c[1]; cosv[2 * q + 1] = c[2]; sinv[2 * q + 1] = c[3]; }
;                 }
; #pragma unroll
;                 for (int bj = 0; bj < 2; ++bj) {
;                     f32x4 v0 = acc[ai][bj][m][0], v1 = acc[ai][bj][m][1];
;                     const int cit = bj * HALF + wc * 32 + fq * 8;
;                     if (do_rope) {
; #pragma unroll
;                         for (int j = 0; j < 4; ++j) {
;                             const float p0 = __shfl_xor(v0[j], 16), p1 = __shfl_xor(v1[j], 16);
;                             const float r0 = v0[j] * cosv[j] + sgn * p0 * sinv[j], r1 = v1[j] * cosv[4 + j] + sgn * p1 * sinv[4 + j];
;                             v0[j] = fq < 2 ? r0 : v0[j]; v1[j] = fq < 2 ? r1 : v1[j];
;                         }
;                     }
;                     if (pn < 3) { v0 = v0 * QSCALE; v1 = v1 * QSCALE; }
;                     u32x4 w; w.x = cvt_pk_bf16(v0[0], v0[1]); w.y = cvt_pk_bf16(v0[2], v0[3]); w.z = cvt_pk_bf16(v1[0], v1[1]); w.w = cvt_pk_bf16(v1[2], v1[3]);
.Lz_fast:
	s_lshl_b32 s98, s48, 9
	v_lshlrev_b32_e32 v164, 1, v158
	v_add_u32_e32 v164, s98, v164
	v_mov_b32_e32 v165, 0
	s_movk_i32 s99, 0x4200
	v_mad_u64_u32 v[166:167], vcc, v187, s99, v[164:165]
	v_lshl_add_u64 v[166:167], s[2:3], 0, v[166:167]
	s_mov_b32 s44, 0
	s_mov_b32 s45, 0
	s_cmp_lt_u32 s48, 3
	s_cbranch_scc1 .Lz_nokv
	s_add_i32 s98, s48, -3
	s_cmp_ge_u32 s98, 3
	s_cselect_b32 s47, 0x400, 0
	s_cselect_b32 s99, 3, 0
	s_sub_i32 s98, s98, s99
	s_and_b32 s99, s18, 15
	s_lshr_b32 s1, s18, 4
	s_cmp_eq_u32 s98, 1
	s_cbranch_scc1 .Lz_g1
	s_cmp_eq_u32 s98, 2
	s_cbranch_scc1 .Lz_g2
	s_cmp_eq_u32 s99, 15
	s_cselect_b32 s45, 1, 0
	s_mov_b32 s46, 0x4020000
	s_movk_i32 s4, 0x80
	s_branch .Lz_gd
.Lz_g1:
	s_cmp_ge_u32 s99, 14
	s_cselect_b32 s44, 1, 0
	s_cselect_b32 s45, 1, 0
	s_mov_b32 s46, 0x4920000
	s_movk_i32 s4, 0x200
	s_branch .Lz_gd
.Lz_g2:
	s_cmp_ge_u32 s99, 8
	s_cselect_b32 s44, 1, 0
	s_cselect_b32 s45, 1, 0
	s_mov_b32 s46, 0x6d20000
	s_movk_i32 s4, 0x800
.Lz_gd:
	s_mul_i32 s1, s1, s4
	s_add_i32 s1, s1, s4
	s_addk_i32 s1, 0xf000
	s_lshl_b32 s1, s1, 11
	s_add_i32 s46, s46, s1
	s_add_i32 s46, s46, s47
	v_and_b32_e32 v164, 0xfff, v187
	v_lshlrev_b32_e32 v164, 11, v164
	v_lshl_add_u32 v164, v158, 2, v164
	v_add_u32_e32 v164, s46, v164
.Lz_nokv:
	s_cmp_lg_u32 s10, 0
	s_cbranch_scc1 .Lz_ropewave
	s_cmp_lt_u32 s48, 3
	s_cbranch_scc0 .Lz_pl_noqs0
	v_mul_f32_e32 v134, s8, v134
	v_mul_f32_e32 v135, s8, v135
	v_mul_f32_e32 v136, s8, v136
	v_mul_f32_e32 v137, s8, v137
	v_mul_f32_e32 v138, s8, v138
	v_mul_f32_e32 v139, s8, v139
	v_mul_f32_e32 v140, s8, v140
	v_mul_f32_e32 v141, s8, v141
	v_mul_f32_e32 v126, s8, v126
	v_mul_f32_e32 v127, s8, v127
	v_mul_f32_e32 v128, s8, v128
	v_mul_f32_e32 v129, s8, v129
	v_mul_f32_e32 v130, s8, v130
	v_mul_f32_e32 v131, s8, v131
	v_mul_f32_e32 v132, s8, v132
	v_mul_f32_e32 v133, s8, v133
.Lz_pl_noqs0:
	v_cvt_pk_bf16_f32 v196, v134, v135
	v_cvt_pk_bf16_f32 v197, v136, v137
	v_cvt_pk_bf16_f32 v198, v138, v139
	v_cvt_pk_bf16_f32 v199, v140, v141
	global_store_dwordx4 v[166:167], v[196:199], off
	v_cvt_pk_bf16_f32 v200, v126, v127
	v_cvt_pk_bf16_f32 v201, v128, v129
	v_cvt_pk_bf16_f32 v202, v130, v131
	v_cvt_pk_bf16_f32 v203, v132, v133
	global_store_dwordx4 v[166:167], v[200:203], off offset:256
	s_cmp_lg_u32 s44, 0
	s_cbranch_scc0 .Lz_pl_nokv0
	global_store_dwordx4 v164, v[134:137], s[96:97]
	global_store_dwordx4 v164, v[138:141], s[96:97] offset:16
	global_store_dwordx4 v164, v[126:129], s[96:97] offset:512
	global_store_dwordx4 v164, v[130:133], s[96:97] offset:528
.Lz_pl_nokv0:
	s_mov_b32 vcc_lo, 0x42000
	s_mov_b32 vcc_hi, 0
	v_lshl_add_u64 v[168:169], v[166:167], 0, vcc
	s_cmp_lt_u32 s48, 3
	s_cbranch_scc0 .Lz_pl_noqs1
	v_mul_f32_e32 v118, s8, v118
	v_mul_f32_e32 v119, s8, v119
	v_mul_f32_e32 v120, s8, v120
	v_mul_f32_e32 v121, s8, v121
	v_mul_f32_e32 v122, s8, v122
	v_mul_f32_e32 v123, s8, v123
	v_mul_f32_e32 v124, s8, v124
	v_mul_f32_e32 v125, s8, v125
	v_mul_f32_e32 v110, s8, v110
	v_mul_f32_e32 v111, s8, v111
	v_mul_f32_e32 v112, s8, v112
	v_mul_f32_e32 v113, s8, v113
	v_mul_f32_e32 v114, s8, v114
	v_mul_f32_e32 v115, s8, v115
	v_mul_f32_e32 v116, s8, v116
	v_mul_f32_e32 v117, s8, v117
.Lz_pl_noqs1:
	v_cvt_pk_bf16_f32 v204, v118, v119
	v_cvt_pk_bf16_f32 v205, v120, v121
	v_cvt_pk_bf16_f32 v206, v122, v123
	v_cvt_pk_bf16_f32 v207, v124, v125
	global_store_dwordx4 v[168:169], v[204:207], off
	v_cvt_pk_bf16_f32 v208, v110, v111
	v_cvt_pk_bf16_f32 v209, v112, v113
	v_cvt_pk_bf16_f32 v210, v114, v115
	v_cvt_pk_bf16_f32 v211, v116, v117
	global_store_dwordx4 v[168:169], v[208:211], off offset:256
	s_cmp_lg_u32 s44, 0
	s_cbranch_scc0 .Lz_pl_nokv1
	v_add_u32_e32 v165, 0x8000, v164
	global_store_dwordx4 v165, v[118:121], s[96:97]
	global_store_dwordx4 v165, v[122:125], s[96:97] offset:16
	global_store_dwordx4 v165, v[110:113], s[96:97] offset:512
	global_store_dwordx4 v165, v[114:117], s[96:97] offset:528
.Lz_pl_nokv1:
	s_mov_b32 vcc_lo, 0x84000
	s_mov_b32 vcc_hi, 0
	v_lshl_add_u64 v[168:169], v[166:167], 0, vcc
	s_cmp_lt_u32 s48, 3
	s_cbranch_scc0 .Lz_pl_noqs2
	v_mul_f32_e32 v106, s8, v106
	v_mul_f32_e32 v107, s8, v107
	v_mul_f32_e32 v108, s8, v108
	v_mul_f32_e32 v109, s8, v109
	v_mul_f32_e32 v102, s8, v102
	v_mul_f32_e32 v103, s8, v103
	v_mul_f32_e32 v104, s8, v104
	v_mul_f32_e32 v105, s8, v105
	v_mul_f32_e32 v98, s8, v98
	v_mul_f32_e32 v99, s8, v99
	v_mul_f32_e32 v100, s8, v100
	v_mul_f32_e32 v101, s8, v101
	v_mul_f32_e32 v94, s8, v94
	v_mul_f32_e32 v95, s8, v95
	v_mul_f32_e32 v96, s8, v96
	v_mul_f32_e32 v97, s8, v97
.Lz_pl_noqs2:
	v_cvt_pk_bf16_f32 v196, v106, v107
	v_cvt_pk_bf16_f32 v197, v108, v109
	v_cvt_pk_bf16_f32 v198, v102, v103
	v_cvt_pk_bf16_f32 v199, v104, v105
	global_store_dwordx4 v[168:169], v[196:199], off
	v_cvt_pk_bf16_f32 v200, v98, v99
	v_cvt_pk_bf16_f32 v201, v100, v101
	v_cvt_pk_bf16_f32 v202, v94, v95
	v_cvt_pk_bf16_f32 v203, v96, v97
	global_store_dwordx4 v[168:169], v[200:203], off offset:256
	s_cmp_lg_u32 s44, 0
	s_cbranch_scc0 .Lz_pl_nokv2
	v_add_u32_e32 v165, 0x10000, v164
	global_store_dwordx4 v165, v[106:109], s[96:97]
	global_store_dwordx4 v165, v[102:105], s[96:97] offset:16
	global_store_dwordx4 v165, v[98:101], s[96:97] offset:512
	global_store_dwordx4 v165, v[94:97], s[96:97] offset:528
.Lz_pl_nokv2:
	s_mov_b32 vcc_lo, 0xc6000
	s_mov_b32 vcc_hi, 0
	v_lshl_add_u64 v[168:169], v[166:167], 0, vcc
	s_cmp_lt_u32 s48, 3
	s_cbranch_scc0 .Lz_pl_noqs3
	v_mul_f32_e32 v86, s8, v86
	v_mul_f32_e32 v87, s8, v87
	v_mul_f32_e32 v88, s8, v88
	v_mul_f32_e32 v89, s8, v89
	v_mul_f32_e32 v90, s8, v90
	v_mul_f32_e32 v91, s8, v91
	v_mul_f32_e32 v92, s8, v92
	v_mul_f32_e32 v93, s8, v93
	v_mul_f32_e32 v78, s8, v78
	v_mul_f32_e32 v79, s8, v79
	v_mul_f32_e32 v80, s8, v80
	v_mul_f32_e32 v81, s8, v81
	v_mul_f32_e32 v82, s8, v82
	v_mul_f32_e32 v83, s8, v83
	v_mul_f32_e32 v84, s8, v84
	v_mul_f32_e32 v85, s8, v85
; __device__ __forceinline__ unsigned cvt_pk_bf16(float lo, float hi) { unsigned r; asm volatile("v_cvt_pk_bf16_f32 %0, %1, %2" : "=v"(r) : "v"(lo), "v"(hi)); return r; }
;     __device__ __forceinline__ void operator()(const f32x4 (&acc)[2][2][4][2], const Unit& u, int wr, int wc, int fr, int fq) const {
;     ...
; #pragma unroll
;                 for (int bj = 0; bj < 2; ++bj) {
;                     f32x4 v0 = acc[ai][bj][m][0], v1 = acc[ai][bj][m][1];
;                     const int cit = bj * HALF + wc * 32 + fq * 8;
;                     if (do_rope) {
; #pragma unroll
;                         for (int j = 0; j < 4; ++j) {
;                             const float p0 = __shfl_xor(v0[j], 16), p1 = __shfl_xor(v1[j], 16);
;                             const float r0 = v0[j] * cosv[j] + sgn * p0 * sinv[j], r1 = v1[j] * cosv[4 + j] + sgn * p1 * sinv[4 + j];
;                             v0[j] = fq < 2 ? r0 : v0[j]; v1[j] = fq < 2 ? r1 : v1[j];
;                         }
;                     }
;                     if (pn < 3) { v0 = v0 * QSCALE; v1 = v1 * QSCALE; }
;                     u32x4 w; w.x = cvt_pk_bf16(v0[0], v0[1]); w.y = cvt_pk_bf16(v0[2], v0[3]); w.z = cvt_pk_bf16(v1[0], v1[1]); w.w = cvt_pk_bf16(v1[2], v1[3]);
;                     *(u32x4*)(Z + (size_t)row * NZ + pn * BM + cit) = w;
;                     if (is_kv) {
;                         float* dst = nullptr;
;                         if (isP && t >= 4096 - W) dst = out + okp + ((size_t)(b * W + t - (4096 - W)) * 2 + kvsel) * 256 + cit;
;                         else if (isS) dst = out + oks + ((size_t)(b * W + W - 1) * 2 + kvsel) * 256 + cit;
;                         if (dst) { *(f32x4*)dst = v0; *(f32x4*)(dst + 4) = v1; }
.Lz_pl_noqs3:
	v_cvt_pk_bf16_f32 v204, v86, v87
	v_cvt_pk_bf16_f32 v205, v88, v89
	v_cvt_pk_bf16_f32 v206, v90, v91
	v_cvt_pk_bf16_f32 v207, v92, v93
	global_store_dwordx4 v[168:169], v[204:207], off
	v_cvt_pk_bf16_f32 v208, v78, v79
	v_cvt_pk_bf16_f32 v209, v80, v81
	v_cvt_pk_bf16_f32 v210, v82, v83
	v_cvt_pk_bf16_f32 v211, v84, v85
	global_store_dwordx4 v[168:169], v[208:211], off offset:256
	s_cmp_lg_u32 s44, 0
	s_cbranch_scc0 .Lz_pl_nokv3
	v_add_u32_e32 v165, 0x18000, v164
	global_store_dwordx4 v165, v[86:89], s[96:97]
	global_store_dwordx4 v165, v[90:93], s[96:97] offset:16
	global_store_dwordx4 v165, v[78:81], s[96:97] offset:512
	global_store_dwordx4 v165, v[82:85], s[96:97] offset:528
.Lz_pl_nokv3:
	s_mov_b32 vcc_lo, 0x210000
	s_mov_b32 vcc_hi, 0
	v_lshl_add_u64 v[168:169], v[166:167], 0, vcc
	s_cmp_lt_u32 s48, 3
	s_cbranch_scc0 .Lz_pl_noqs4
	v_mul_f32_e32 v70, s8, v70
	v_mul_f32_e32 v71, s8, v71
	v_mul_f32_e32 v72, s8, v72
	v_mul_f32_e32 v73, s8, v73
	v_mul_f32_e32 v74, s8, v74
	v_mul_f32_e32 v75, s8, v75
	v_mul_f32_e32 v76, s8, v76
	v_mul_f32_e32 v77, s8, v77
	v_mul_f32_e32 v62, s8, v62
	v_mul_f32_e32 v63, s8, v63
	v_mul_f32_e32 v64, s8, v64
	v_mul_f32_e32 v65, s8, v65
	v_mul_f32_e32 v66, s8, v66
	v_mul_f32_e32 v67, s8, v67
	v_mul_f32_e32 v68, s8, v68
	v_mul_f32_e32 v69, s8, v69
.Lz_pl_noqs4:
	v_cvt_pk_bf16_f32 v196, v70, v71
	v_cvt_pk_bf16_f32 v197, v72, v73
	v_cvt_pk_bf16_f32 v198, v74, v75
	v_cvt_pk_bf16_f32 v199, v76, v77
	global_store_dwordx4 v[168:169], v[196:199], off
	v_cvt_pk_bf16_f32 v200, v62, v63
	v_cvt_pk_bf16_f32 v201, v64, v65
	v_cvt_pk_bf16_f32 v202, v66, v67
	v_cvt_pk_bf16_f32 v203, v68, v69
	global_store_dwordx4 v[168:169], v[200:203], off offset:256
	s_cmp_lg_u32 s45, 0
	s_cbranch_scc0 .Lz_pl_nokv4
	v_add_u32_e32 v165, 0x40000, v164
	global_store_dwordx4 v165, v[70:73], s[96:97]
	global_store_dwordx4 v165, v[74:77], s[96:97] offset:16
	global_store_dwordx4 v165, v[62:65], s[96:97] offset:512
	global_store_dwordx4 v165, v[66:69], s[96:97] offset:528
.Lz_pl_nokv4:
	s_mov_b32 vcc_lo, 0x252000
	s_mov_b32 vcc_hi, 0
	v_lshl_add_u64 v[168:169], v[166:167], 0, vcc
	s_cmp_lt_u32 s48, 3
	s_cbranch_scc0 .Lz_pl_noqs5
	v_mul_f32_e32 v54, s8, v54
	v_mul_f32_e32 v55, s8, v55
	v_mul_f32_e32 v56, s8, v56
	v_mul_f32_e32 v57, s8, v57
	v_mul_f32_e32 v58, s8, v58
	v_mul_f32_e32 v59, s8, v59
	v_mul_f32_e32 v60, s8, v60
	v_mul_f32_e32 v61, s8, v61
	v_mul_f32_e32 v42, s8, v42
	v_mul_f32_e32 v43, s8, v43
	v_mul_f32_e32 v44, s8, v44
	v_mul_f32_e32 v45, s8, v45
	v_mul_f32_e32 v46, s8, v46
	v_mul_f32_e32 v47, s8, v47
	v_mul_f32_e32 v48, s8, v48
	v_mul_f32_e32 v49, s8, v49
.Lz_pl_noqs5:
	v_cvt_pk_bf16_f32 v204, v54, v55
	v_cvt_pk_bf16_f32 v205, v56, v57
	v_cvt_pk_bf16_f32 v206, v58, v59
	v_cvt_pk_bf16_f32 v207, v60, v61
	global_store_dwordx4 v[168:169], v[204:207], off
	v_cvt_pk_bf16_f32 v208, v42, v43
	v_cvt_pk_bf16_f32 v209, v44, v45
	v_cvt_pk_bf16_f32 v210, v46, v47
	v_cvt_pk_bf16_f32 v211, v48, v49
	global_store_dwordx4 v[168:169], v[208:211], off offset:256
	s_cmp_lg_u32 s45, 0
	s_cbranch_scc0 .Lz_pl_nokv5
	v_add_u32_e32 v165, 0x48000, v164
	global_store_dwordx4 v165, v[54:57], s[96:97]
	global_store_dwordx4 v165, v[58:61], s[96:97] offset:16
	global_store_dwordx4 v165, v[42:45], s[96:97] offset:512
	global_store_dwordx4 v165, v[46:49], s[96:97] offset:528
.Lz_pl_nokv5:
	s_mov_b32 vcc_lo, 0x294000
	s_mov_b32 vcc_hi, 0
	v_lshl_add_u64 v[168:169], v[166:167], 0, vcc
	s_cmp_lt_u32 s48, 3
	s_cbranch_scc0 .Lz_pl_noqs6
	v_mul_f32_e32 v38, s8, v38
	v_mul_f32_e32 v39, s8, v39
	v_mul_f32_e32 v40, s8, v40
	v_mul_f32_e32 v41, s8, v41
	v_mul_f32_e32 v34, s8, v34
	v_mul_f32_e32 v35, s8, v35
	v_mul_f32_e32 v36, s8, v36
	v_mul_f32_e32 v37, s8, v37
	v_mul_f32_e32 v30, s8, v30
	v_mul_f32_e32 v31, s8, v31
	v_mul_f32_e32 v32, s8, v32
	v_mul_f32_e32 v33, s8, v33
	v_mul_f32_e32 v26, s8, v26
	v_mul_f32_e32 v27, s8, v27
	v_mul_f32_e32 v28, s8, v28
	v_mul_f32_e32 v29, s8, v29
.Lz_pl_noqs6:
	v_cvt_pk_bf16_f32 v196, v38, v39
	v_cvt_pk_bf16_f32 v197, v40, v41
	v_cvt_pk_bf16_f32 v198, v34, v35
	v_cvt_pk_bf16_f32 v199, v36, v37
	global_store_dwordx4 v[168:169], v[196:199], off
	v_cvt_pk_bf16_f32 v200, v30, v31
	v_cvt_pk_bf16_f32 v201, v32, v33
	v_cvt_pk_bf16_f32 v202, v26, v27
	v_cvt_pk_bf16_f32 v203, v28, v29
	global_store_dwordx4 v[168:169], v[200:203], off offset:256
	s_cmp_lg_u32 s45, 0
	s_cbranch_scc0 .Lz_pl_nokv6
	v_add_u32_e32 v165, 0x50000, v164
	global_store_dwordx4 v165, v[38:41], s[96:97]
	global_store_dwordx4 v165, v[34:37], s[96:97] offset:16
	global_store_dwordx4 v165, v[30:33], s[96:97] offset:512
	global_store_dwordx4 v165, v[26:29], s[96:97] offset:528
.Lz_pl_nokv6:
	s_mov_b32 vcc_lo, 0x2d6000
	s_mov_b32 vcc_hi, 0
	v_lshl_add_u64 v[168:169], v[166:167], 0, vcc
	s_cmp_lt_u32 s48, 3
	s_cbranch_scc0 .Lz_pl_noqs7
	v_mul_f32_e32 v18, s8, v18
	v_mul_f32_e32 v19, s8, v19
	v_mul_f32_e32 v20, s8, v20
	v_mul_f32_e32 v21, s8, v21
	v_mul_f32_e32 v22, s8, v22
	v_mul_f32_e32 v23, s8, v23
	v_mul_f32_e32 v24, s8, v24
	v_mul_f32_e32 v25, s8, v25
	v_mul_f32_e32 v14, s8, v14
	v_mul_f32_e32 v15, s8, v15
	v_mul_f32_e32 v16, s8, v16
	v_mul_f32_e32 v17, s8, v17
	v_mul_f32_e32 v10, s8, v10
	v_mul_f32_e32 v11, s8, v11
	v_mul_f32_e32 v12, s8, v12
	v_mul_f32_e32 v13, s8, v13
.Lz_pl_noqs7:
	v_cvt_pk_bf16_f32 v204, v18, v19
	v_cvt_pk_bf16_f32 v205, v20, v21
	v_cvt_pk_bf16_f32 v206, v22, v23
	v_cvt_pk_bf16_f32 v207, v24, v25
	global_store_dwordx4 v[168:169], v[204:207], off
	v_cvt_pk_bf16_f32 v208, v14, v15
	v_cvt_pk_bf16_f32 v209, v16, v17
	v_cvt_pk_bf16_f32 v210, v10, v11
	v_cvt_pk_bf16_f32 v211, v12, v13
	global_store_dwordx4 v[168:169], v[208:211], off offset:256
	s_cmp_lg_u32 s45, 0
	s_cbranch_scc0 .Lz_pl_nokv7
	v_add_u32_e32 v165, 0x58000, v164
	global_store_dwordx4 v165, v[18:21], s[96:97]
	global_store_dwordx4 v165, v[22:25], s[96:97] offset:16
	global_store_dwordx4 v165, v[14:17], s[96:97] offset:512
	global_store_dwordx4 v165, v[10:13], s[96:97] offset:528
; __device__ __forceinline__ unsigned cvt_pk_bf16(float lo, float hi) { unsigned r; asm volatile("v_cvt_pk_bf16_f32 %0, %1, %2" : "=v"(r) : "v"(lo), "v"(hi)); return r; }
;     __device__ __forceinline__ void operator()(const f32x4 (&acc)[2][2][4][2], const Unit& u, int wr, int wc, int fr, int fq) const {
;     ...
;                 if (do_rope) {
;                     const f32x4* cs = (const f32x4*)(rope + (size_t)(isP ? t : 4096) * 16);
; #pragma unroll
;                     for (int q = 0; q < 4; ++q) { const f32x4 c = cs[q]; cosv[2 * q] = c[0]; sinv[2 * q] = c[1]; cosv[2 * q + 1] = c[2]; sinv[2 * q + 1] = c[3]; }
;                 }
; #pragma unroll
;                 for (int bj = 0; bj < 2; ++bj) {
;                     f32x4 v0 = acc[ai][bj][m][0], v1 = acc[ai][bj][m][1];
;                     const int cit = bj * HALF + wc * 32 + fq * 8;
;                     if (do_rope) {
; #pragma unroll
;                         for (int j = 0; j < 4; ++j) {
;                             const float p0 = __shfl_xor(v0[j], 16), p1 = __shfl_xor(v1[j], 16);
;                             const float r0 = v0[j] * cosv[j] + sgn * p0 * sinv[j], r1 = v1[j] * cosv[4 + j] + sgn * p1 * sinv[4 + j];
;                             v0[j] = fq < 2 ? r0 : v0[j]; v1[j] = fq < 2 ? r1 : v1[j];
;                         }
;                     }
;                     if (pn < 3) { v0 = v0 * QSCALE; v1 = v1 * QSCALE; }
;                     u32x4 w; w.x = cvt_pk_bf16(v0[0], v0[1]); w.y = cvt_pk_bf16(v0[2], v0[3]); w.z = cvt_pk_bf16(v1[0], v1[1]); w.w = cvt_pk_bf16(v1[2], v1[3]);
;                     *(u32x4*)(Z + (size_t)row * NZ + pn * BM + cit) = w;
.Lz_pl_nokv7:
	s_branch .LBB0_297
.Lz_ropewave:
	v_and_b32_e32 v170, 0xfff, v187
	v_lshlrev_b32_e32 v170, 6, v170
	v_mov_b32_e32 v171, 64
	s_cmp_eq_u32 s18, 64
	s_cbranch_scc0 .Lz_rw_p
	v_mov_b32_e32 v170, 0x40000
	v_mov_b32_e32 v171, 0
.Lz_rw_p:
	v_and_b32_e32 v8, 32, v183
	v_cmp_eq_u32_e32 vcc, 0, v8
	s_nop 1
	v_cndmask_b32_e32 v170, 0, v170, vcc
	v_cndmask_b32_e32 v171, 0, v171, vcc
	global_load_dwordx4 v[196:199], v170, s[34:35]
	global_load_dwordx4 v[200:203], v170, s[34:35] offset:16
	global_load_dwordx4 v[204:207], v170, s[34:35] offset:32
	global_load_dwordx4 v[208:211], v170, s[34:35] offset:48
	s_movk_i32 s98, 0x10
	v_mad_u32_u24 v9, v171, s98, v170
	global_load_dwordx4 v[212:215], v9, s[34:35]
	global_load_dwordx4 v[216:219], v9, s[34:35] offset:16
	global_load_dwordx4 v[220:223], v9, s[34:35] offset:32
	global_load_dwordx4 v[224:227], v9, s[34:35] offset:48
	s_movk_i32 s98, 0x20
	v_mad_u32_u24 v8, v171, s98, v170
	global_load_dwordx4 v[0:3], v8, s[34:35]
	global_load_dwordx4 v[4:7], v8, s[34:35] offset:16
	global_load_dwordx4 v[176:179], v8, s[34:35] offset:32
	global_load_dwordx4 v[172:175], v8, s[34:35] offset:48
	s_waitcnt vmcnt(8)
	v_permlane16_swap_b32_e32 v134, v126
	v_permlane16_swap_b32_e32 v135, v127
	v_permlane16_swap_b32_e32 v136, v128
	v_permlane16_swap_b32_e32 v137, v129
	v_permlane16_swap_b32_e32 v138, v130
	v_permlane16_swap_b32_e32 v139, v131
	v_permlane16_swap_b32_e32 v140, v132
	v_permlane16_swap_b32_e32 v141, v133
	v_mul_f32_e32 v188, v126, v197
	v_mul_f32_e32 v197, v134, v197
	v_mul_f32_e32 v189, v127, v199
	v_mul_f32_e32 v199, v135, v199
	v_mul_f32_e32 v190, v128, v201
	v_mul_f32_e32 v201, v136, v201
	v_mul_f32_e32 v191, v129, v203
	v_mul_f32_e32 v203, v137, v203
	v_mul_f32_e32 v192, v130, v205
	v_mul_f32_e32 v205, v138, v205
	v_mul_f32_e32 v193, v131, v207
	v_mul_f32_e32 v207, v139, v207
	v_mul_f32_e32 v194, v132, v209
	v_mul_f32_e32 v209, v140, v209
	v_mul_f32_e32 v195, v133, v211
	v_mul_f32_e32 v211, v141, v211
	v_fma_f32 v134, v134, v196, -v188
	v_fma_f32 v126, v126, v196, v197
	v_fma_f32 v135, v135, v198, -v189
	v_fma_f32 v127, v127, v198, v199
	v_fma_f32 v136, v136, v200, -v190
	v_fma_f32 v128, v128, v200, v201
	v_fma_f32 v137, v137, v202, -v191
	v_fma_f32 v129, v129, v202, v203
	v_fma_f32 v138, v138, v204, -v192
	v_fma_f32 v130, v130, v204, v205
	v_fma_f32 v139, v139, v206, -v193
	v_fma_f32 v131, v131, v206, v207
	v_fma_f32 v140, v140, v208, -v194
	v_fma_f32 v132, v132, v208, v209
	v_fma_f32 v141, v141, v210, -v195
	v_fma_f32 v133, v133, v210, v211
	v_permlane16_swap_b32_e32 v134, v126
	v_permlane16_swap_b32_e32 v135, v127
	v_permlane16_swap_b32_e32 v136, v128
	v_permlane16_swap_b32_e32 v137, v129
	v_permlane16_swap_b32_e32 v138, v130
	v_permlane16_swap_b32_e32 v139, v131
	v_permlane16_swap_b32_e32 v140, v132
	v_permlane16_swap_b32_e32 v141, v133
	s_cmp_lt_u32 s48, 3
	s_cbranch_scc0 .Lz_rw_noqs0
	v_mul_f32_e32 v134, s8, v134
	v_mul_f32_e32 v135, s8, v135
	v_mul_f32_e32 v136, s8, v136
	v_mul_f32_e32 v137, s8, v137
	v_mul_f32_e32 v138, s8, v138
	v_mul_f32_e32 v139, s8, v139
	v_mul_f32_e32 v140, s8, v140
	v_mul_f32_e32 v141, s8, v141
	v_mul_f32_e32 v126, s8, v126
	v_mul_f32_e32 v127, s8, v127
	v_mul_f32_e32 v128, s8, v128
	v_mul_f32_e32 v129, s8, v129
	v_mul_f32_e32 v130, s8, v130
	v_mul_f32_e32 v131, s8, v131
	v_mul_f32_e32 v132, s8, v132
	v_mul_f32_e32 v133, s8, v133
.Lz_rw_noqs0:
	v_cvt_pk_bf16_f32 v188, v134, v135
	v_cvt_pk_bf16_f32 v189, v136, v137
	v_cvt_pk_bf16_f32 v190, v138, v139
	v_cvt_pk_bf16_f32 v191, v140, v141
	global_store_dwordx4 v[166:167], v[188:191], off
	v_cvt_pk_bf16_f32 v192, v126, v127
	v_cvt_pk_bf16_f32 v193, v128, v129
	v_cvt_pk_bf16_f32 v194, v130, v131
	v_cvt_pk_bf16_f32 v195, v132, v133
	global_store_dwordx4 v[166:167], v[192:195], off offset:256
	s_cmp_lg_u32 s44, 0
	s_cbranch_scc0 .Lz_rw_nokv0
	global_store_dwordx4 v164, v[134:137], s[96:97]
	global_store_dwordx4 v164, v[138:141], s[96:97] offset:16
	global_store_dwordx4 v164, v[126:129], s[96:97] offset:512
	global_store_dwordx4 v164, v[130:133], s[96:97] offset:528
.Lz_rw_nokv0:
	s_movk_i32 s98, 0x30
	v_mad_u32_u24 v9, v171, s98, v170
	global_load_dwordx4 v[134:137], v9, s[34:35]
	global_load_dwordx4 v[138:141], v9, s[34:35] offset:16
	global_load_dwordx4 v[126:129], v9, s[34:35] offset:32
	global_load_dwordx4 v[130:133], v9, s[34:35] offset:48
	s_mov_b32 vcc_lo, 0x42000
	s_mov_b32 vcc_hi, 0
	v_lshl_add_u64 v[168:169], v[166:167], 0, vcc
	s_waitcnt vmcnt(10)
	v_permlane16_swap_b32_e32 v118, v110
	v_permlane16_swap_b32_e32 v119, v111
	v_permlane16_swap_b32_e32 v120, v112
	v_permlane16_swap_b32_e32 v121, v113
	v_permlane16_swap_b32_e32 v122, v114
	v_permlane16_swap_b32_e32 v123, v115
	v_permlane16_swap_b32_e32 v124, v116
	v_permlane16_swap_b32_e32 v125, v117
	v_mul_f32_e32 v188, v110, v213
	v_mul_f32_e32 v213, v118, v213
	v_mul_f32_e32 v189, v111, v215
	v_mul_f32_e32 v215, v119, v215
	v_mul_f32_e32 v190, v112, v217
	v_mul_f32_e32 v217, v120, v217
	v_mul_f32_e32 v191, v113, v219
	v_mul_f32_e32 v219, v121, v219
	v_mul_f32_e32 v192, v114, v221
	v_mul_f32_e32 v221, v122, v221
	v_mul_f32_e32 v193, v115, v223
	v_mul_f32_e32 v223, v123, v223
	v_mul_f32_e32 v194, v116, v225
	v_mul_f32_e32 v225, v124, v225
	v_mul_f32_e32 v195, v117, v227
	v_mul_f32_e32 v227, v125, v227
	v_fma_f32 v118, v118, v212, -v188
	v_fma_f32 v110, v110, v212, v213
	v_fma_f32 v119, v119, v214, -v189
	v_fma_f32 v111, v111, v214, v215
	v_fma_f32 v120, v120, v216, -v190
	v_fma_f32 v112, v112, v216, v217
	v_fma_f32 v121, v121, v218, -v191
	v_fma_f32 v113, v113, v218, v219
	v_fma_f32 v122, v122, v220, -v192
	v_fma_f32 v114, v114, v220, v221
	v_fma_f32 v123, v123, v222, -v193
	v_fma_f32 v115, v115, v222, v223
	v_fma_f32 v124, v124, v224, -v194
	v_fma_f32 v116, v116, v224, v225
	v_fma_f32 v125, v125, v226, -v195
	v_fma_f32 v117, v117, v226, v227
	v_permlane16_swap_b32_e32 v118, v110
	v_permlane16_swap_b32_e32 v119, v111
	v_permlane16_swap_b32_e32 v120, v112
	v_permlane16_swap_b32_e32 v121, v113
	v_permlane16_swap_b32_e32 v122, v114
	v_permlane16_swap_b32_e32 v123, v115
	v_permlane16_swap_b32_e32 v124, v116
	v_permlane16_swap_b32_e32 v125, v117
	s_cmp_lt_u32 s48, 3
	s_cbranch_scc0 .Lz_rw_noqs1
	v_mul_f32_e32 v118, s8, v118
	v_mul_f32_e32 v119, s8, v119
	v_mul_f32_e32 v120, s8, v120
	v_mul_f32_e32 v121, s8, v121
	v_mul_f32_e32 v122, s8, v122
	v_mul_f32_e32 v123, s8, v123
	v_mul_f32_e32 v124, s8, v124
	v_mul_f32_e32 v125, s8, v125
	v_mul_f32_e32 v110, s8, v110
	v_mul_f32_e32 v111, s8, v111
	v_mul_f32_e32 v112, s8, v112
	v_mul_f32_e32 v113, s8, v113
	v_mul_f32_e32 v114, s8, v114
	v_mul_f32_e32 v115, s8, v115
	v_mul_f32_e32 v116, s8, v116
	v_mul_f32_e32 v117, s8, v117
; __device__ __forceinline__ unsigned cvt_pk_bf16(float lo, float hi) { unsigned r; asm volatile("v_cvt_pk_bf16_f32 %0, %1, %2" : "=v"(r) : "v"(lo), "v"(hi)); return r; }
;     __device__ __forceinline__ void operator()(const f32x4 (&acc)[2][2][4][2], const Unit& u, int wr, int wc, int fr, int fq) const {
;     ...
;                 if (do_rope) {
;                     const f32x4* cs = (const f32x4*)(rope + (size_t)(isP ? t : 4096) * 16);
; #pragma unroll
;                     for (int q = 0; q < 4; ++q) { const f32x4 c = cs[q]; cosv[2 * q] = c[0]; sinv[2 * q] = c[1]; cosv[2 * q + 1] = c[2]; sinv[2 * q + 1] = c[3]; }
;                 }
; #pragma unroll
;                 for (int bj = 0; bj < 2; ++bj) {
;                     f32x4 v0 = acc[ai][bj][m][0], v1 = acc[ai][bj][m][1];
;                     const int cit = bj * HALF + wc * 32 + fq * 8;
;                     if (do_rope) {
; #pragma unroll
;                         for (int j = 0; j < 4; ++j) {
;                             const float p0 = __shfl_xor(v0[j], 16), p1 = __shfl_xor(v1[j], 16);
;                             const float r0 = v0[j] * cosv[j] + sgn * p0 * sinv[j], r1 = v1[j] * cosv[4 + j] + sgn * p1 * sinv[4 + j];
;                             v0[j] = fq < 2 ? r0 : v0[j]; v1[j] = fq < 2 ? r1 : v1[j];
;                         }
;                     }
;                     if (pn < 3) { v0 = v0 * QSCALE; v1 = v1 * QSCALE; }
;                     u32x4 w; w.x = cvt_pk_bf16(v0[0], v0[1]); w.y = cvt_pk_bf16(v0[2], v0[3]); w.z = cvt_pk_bf16(v1[0], v1[1]); w.w = cvt_pk_bf16(v1[2], v1[3]);
;                     *(u32x4*)(Z + (size_t)row * NZ + pn * BM + cit) = w;
;                     if (is_kv) {
;                         float* dst = nullptr;
;                         if (isP && t >= 4096 - W) dst = out + okp + ((size_t)(b * W + t - (4096 - W)) * 2 + kvsel) * 256 + cit;
;                         else if (isS) dst = out + oks + ((size_t)(b * W + W - 1) * 2 + kvsel) * 256 + cit;
;                         if (dst) { *(f32x4*)dst = v0; *(f32x4*)(dst + 4) = v1; }
.Lz_rw_noqs1:
	v_cvt_pk_bf16_f32 v188, v118, v119
	v_cvt_pk_bf16_f32 v189, v120, v121
	v_cvt_pk_bf16_f32 v190, v122, v123
	v_cvt_pk_bf16_f32 v191, v124, v125
	global_store_dwordx4 v[168:169], v[188:191], off
	v_cvt_pk_bf16_f32 v192, v110, v111
	v_cvt_pk_bf16_f32 v193, v112, v113
	v_cvt_pk_bf16_f32 v194, v114, v115
	v_cvt_pk_bf16_f32 v195, v116, v117
	global_store_dwordx4 v[168:169], v[192:195], off offset:256
	s_cmp_lg_u32 s44, 0
	s_cbranch_scc0 .Lz_rw_nokv1
	v_add_u32_e32 v165, 0x8000, v164
	global_store_dwordx4 v165, v[118:121], s[96:97]
	global_store_dwordx4 v165, v[122:125], s[96:97] offset:16
	global_store_dwordx4 v165, v[110:113], s[96:97] offset:512
	global_store_dwordx4 v165, v[114:117], s[96:97] offset:528
.Lz_rw_nokv1:
	s_movk_i32 s98, 0x80
	v_mad_u32_u24 v8, v171, s98, v170
	global_load_dwordx4 v[118:121], v8, s[34:35]
	global_load_dwordx4 v[122:125], v8, s[34:35] offset:16
	global_load_dwordx4 v[110:113], v8, s[34:35] offset:32
	global_load_dwordx4 v[114:117], v8, s[34:35] offset:48
	s_mov_b32 vcc_lo, 0x84000
	s_mov_b32 vcc_hi, 0
	v_lshl_add_u64 v[168:169], v[166:167], 0, vcc
	s_waitcnt vmcnt(12)
	v_permlane16_swap_b32_e32 v106, v98
	v_permlane16_swap_b32_e32 v107, v99
	v_permlane16_swap_b32_e32 v108, v100
	v_permlane16_swap_b32_e32 v109, v101
	v_permlane16_swap_b32_e32 v102, v94
	v_permlane16_swap_b32_e32 v103, v95
	v_permlane16_swap_b32_e32 v104, v96
	v_permlane16_swap_b32_e32 v105, v97
	v_mul_f32_e32 v188, v98, v1
	v_mul_f32_e32 v1, v106, v1
	v_mul_f32_e32 v189, v99, v3
	v_mul_f32_e32 v3, v107, v3
	v_mul_f32_e32 v190, v100, v5
	v_mul_f32_e32 v5, v108, v5
	v_mul_f32_e32 v191, v101, v7
	v_mul_f32_e32 v7, v109, v7
	v_mul_f32_e32 v192, v94, v177
	v_mul_f32_e32 v177, v102, v177
	v_mul_f32_e32 v193, v95, v179
	v_mul_f32_e32 v179, v103, v179
	v_mul_f32_e32 v194, v96, v173
	v_mul_f32_e32 v173, v104, v173
	v_mul_f32_e32 v195, v97, v175
	v_mul_f32_e32 v175, v105, v175
	v_fma_f32 v106, v106, v0, -v188
	v_fma_f32 v98, v98, v0, v1
	v_fma_f32 v107, v107, v2, -v189
	v_fma_f32 v99, v99, v2, v3
	v_fma_f32 v108, v108, v4, -v190
	v_fma_f32 v100, v100, v4, v5
	v_fma_f32 v109, v109, v6, -v191
	v_fma_f32 v101, v101, v6, v7
	v_fma_f32 v102, v102, v176, -v192
	v_fma_f32 v94, v94, v176, v177
	v_fma_f32 v103, v103, v178, -v193
	v_fma_f32 v95, v95, v178, v179
	v_fma_f32 v104, v104, v172, -v194
	v_fma_f32 v96, v96, v172, v173
	v_fma_f32 v105, v105, v174, -v195
	v_fma_f32 v97, v97, v174, v175
	v_permlane16_swap_b32_e32 v106, v98
	v_permlane16_swap_b32_e32 v107, v99
	v_permlane16_swap_b32_e32 v108, v100
	v_permlane16_swap_b32_e32 v109, v101
	v_permlane16_swap_b32_e32 v102, v94
	v_permlane16_swap_b32_e32 v103, v95
	v_permlane16_swap_b32_e32 v104, v96
	v_permlane16_swap_b32_e32 v105, v97
	s_cmp_lt_u32 s48, 3
	s_cbranch_scc0 .Lz_rw_noqs2
	v_mul_f32_e32 v106, s8, v106
	v_mul_f32_e32 v107, s8, v107
	v_mul_f32_e32 v108, s8, v108
	v_mul_f32_e32 v109, s8, v109
	v_mul_f32_e32 v102, s8, v102
	v_mul_f32_e32 v103, s8, v103
	v_mul_f32_e32 v104, s8, v104
	v_mul_f32_e32 v105, s8, v105
	v_mul_f32_e32 v98, s8, v98
	v_mul_f32_e32 v99, s8, v99
	v_mul_f32_e32 v100, s8, v100
	v_mul_f32_e32 v101, s8, v101
	v_mul_f32_e32 v94, s8, v94
	v_mul_f32_e32 v95, s8, v95
	v_mul_f32_e32 v96, s8, v96
	v_mul_f32_e32 v97, s8, v97
.Lz_rw_noqs2:
	v_cvt_pk_bf16_f32 v188, v106, v107
	v_cvt_pk_bf16_f32 v189, v108, v109
	v_cvt_pk_bf16_f32 v190, v102, v103
	v_cvt_pk_bf16_f32 v191, v104, v105
	global_store_dwordx4 v[168:169], v[188:191], off
	v_cvt_pk_bf16_f32 v192, v98, v99
	v_cvt_pk_bf16_f32 v193, v100, v101
	v_cvt_pk_bf16_f32 v194, v94, v95
	v_cvt_pk_bf16_f32 v195, v96, v97
	global_store_dwordx4 v[168:169], v[192:195], off offset:256
	s_cmp_lg_u32 s44, 0
	s_cbranch_scc0 .Lz_rw_nokv2
	v_add_u32_e32 v165, 0x10000, v164
	global_store_dwordx4 v165, v[106:109], s[96:97]
	global_store_dwordx4 v165, v[102:105], s[96:97] offset:16
	global_store_dwordx4 v165, v[98:101], s[96:97] offset:512
	global_store_dwordx4 v165, v[94:97], s[96:97] offset:528
.Lz_rw_nokv2:
	s_movk_i32 s98, 0x90
	v_mad_u32_u24 v9, v171, s98, v170
	global_load_dwordx4 v[106:109], v9, s[34:35]
	global_load_dwordx4 v[102:105], v9, s[34:35] offset:16
	global_load_dwordx4 v[98:101], v9, s[34:35] offset:32
	global_load_dwordx4 v[94:97], v9, s[34:35] offset:48
	s_mov_b32 vcc_lo, 0xc6000
	s_mov_b32 vcc_hi, 0
	v_lshl_add_u64 v[168:169], v[166:167], 0, vcc
	s_waitcnt vmcnt(12)
	v_permlane16_swap_b32_e32 v86, v78
	v_permlane16_swap_b32_e32 v87, v79
	v_permlane16_swap_b32_e32 v88, v80
	v_permlane16_swap_b32_e32 v89, v81
	v_permlane16_swap_b32_e32 v90, v82
	v_permlane16_swap_b32_e32 v91, v83
	v_permlane16_swap_b32_e32 v92, v84
	v_permlane16_swap_b32_e32 v93, v85
	v_mul_f32_e32 v188, v78, v135
	v_mul_f32_e32 v135, v86, v135
	v_mul_f32_e32 v189, v79, v137
	v_mul_f32_e32 v137, v87, v137
	v_mul_f32_e32 v190, v80, v139
	v_mul_f32_e32 v139, v88, v139
	v_mul_f32_e32 v191, v81, v141
	v_mul_f32_e32 v141, v89, v141
	v_mul_f32_e32 v192, v82, v127
	v_mul_f32_e32 v127, v90, v127
	v_mul_f32_e32 v193, v83, v129
	v_mul_f32_e32 v129, v91, v129
	v_mul_f32_e32 v194, v84, v131
	v_mul_f32_e32 v131, v92, v131
	v_mul_f32_e32 v195, v85, v133
	v_mul_f32_e32 v133, v93, v133
	v_fma_f32 v86, v86, v134, -v188
	v_fma_f32 v78, v78, v134, v135
	v_fma_f32 v87, v87, v136, -v189
	v_fma_f32 v79, v79, v136, v137
	v_fma_f32 v88, v88, v138, -v190
	v_fma_f32 v80, v80, v138, v139
	v_fma_f32 v89, v89, v140, -v191
	v_fma_f32 v81, v81, v140, v141
	v_fma_f32 v90, v90, v126, -v192
	v_fma_f32 v82, v82, v126, v127
	v_fma_f32 v91, v91, v128, -v193
	v_fma_f32 v83, v83, v128, v129
	v_fma_f32 v92, v92, v130, -v194
	v_fma_f32 v84, v84, v130, v131
	v_fma_f32 v93, v93, v132, -v195
	v_fma_f32 v85, v85, v132, v133
	v_permlane16_swap_b32_e32 v86, v78
	v_permlane16_swap_b32_e32 v87, v79
	v_permlane16_swap_b32_e32 v88, v80
	v_permlane16_swap_b32_e32 v89, v81
	v_permlane16_swap_b32_e32 v90, v82
	v_permlane16_swap_b32_e32 v91, v83
	v_permlane16_swap_b32_e32 v92, v84
	v_permlane16_swap_b32_e32 v93, v85
	s_cmp_lt_u32 s48, 3
	s_cbranch_scc0 .Lz_rw_noqs3
	v_mul_f32_e32 v86, s8, v86
	v_mul_f32_e32 v87, s8, v87
	v_mul_f32_e32 v88, s8, v88
	v_mul_f32_e32 v89, s8, v89
	v_mul_f32_e32 v90, s8, v90
	v_mul_f32_e32 v91, s8, v91
	v_mul_f32_e32 v92, s8, v92
	v_mul_f32_e32 v93, s8, v93
	v_mul_f32_e32 v78, s8, v78
	v_mul_f32_e32 v79, s8, v79
	v_mul_f32_e32 v80, s8, v80
	v_mul_f32_e32 v81, s8, v81
	v_mul_f32_e32 v82, s8, v82
	v_mul_f32_e32 v83, s8, v83
	v_mul_f32_e32 v84, s8, v84
	v_mul_f32_e32 v85, s8, v85
; __device__ __forceinline__ unsigned cvt_pk_bf16(float lo, float hi) { unsigned r; asm volatile("v_cvt_pk_bf16_f32 %0, %1, %2" : "=v"(r) : "v"(lo), "v"(hi)); return r; }
;     __device__ __forceinline__ void operator()(const f32x4 (&acc)[2][2][4][2], const Unit& u, int wr, int wc, int fr, int fq) const {
;     ...
;                 if (do_rope) {
;                     const f32x4* cs = (const f32x4*)(rope + (size_t)(isP ? t : 4096) * 16);
; #pragma unroll
;                     for (int q = 0; q < 4; ++q) { const f32x4 c = cs[q]; cosv[2 * q] = c[0]; sinv[2 * q] = c[1]; cosv[2 * q + 1] = c[2]; sinv[2 * q + 1] = c[3]; }
;                 }
; #pragma unroll
;                 for (int bj = 0; bj < 2; ++bj) {
;                     f32x4 v0 = acc[ai][bj][m][0], v1 = acc[ai][bj][m][1];
;                     const int cit = bj * HALF + wc * 32 + fq * 8;
;                     if (do_rope) {
; #pragma unroll
;                         for (int j = 0; j < 4; ++j) {
;                             const float p0 = __shfl_xor(v0[j], 16), p1 = __shfl_xor(v1[j], 16);
;                             const float r0 = v0[j] * cosv[j] + sgn * p0 * sinv[j], r1 = v1[j] * cosv[4 + j] + sgn * p1 * sinv[4 + j];
;                             v0[j] = fq < 2 ? r0 : v0[j]; v1[j] = fq < 2 ? r1 : v1[j];
;                         }
;                     }
;                     if (pn < 3) { v0 = v0 * QSCALE; v1 = v1 * QSCALE; }
;                     u32x4 w; w.x = cvt_pk_bf16(v0[0], v0[1]); w.y = cvt_pk_bf16(v0[2], v0[3]); w.z = cvt_pk_bf16(v1[0], v1[1]); w.w = cvt_pk_bf16(v1[2], v1[3]);
;                     *(u32x4*)(Z + (size_t)row * NZ + pn * BM + cit) = w;
;                     if (is_kv) {
;                         float* dst = nullptr;
;                         if (isP && t >= 4096 - W) dst = out + okp + ((size_t)(b * W + t - (4096 - W)) * 2 + kvsel) * 256 + cit;
;                         else if (isS) dst = out + oks + ((size_t)(b * W + W - 1) * 2 + kvsel) * 256 + cit;
;                         if (dst) { *(f32x4*)dst = v0; *(f32x4*)(dst + 4) = v1; }
.Lz_rw_noqs3:
	v_cvt_pk_bf16_f32 v188, v86, v87
	v_cvt_pk_bf16_f32 v189, v88, v89
	v_cvt_pk_bf16_f32 v190, v90, v91
	v_cvt_pk_bf16_f32 v191, v92, v93
	global_store_dwordx4 v[168:169], v[188:191], off
	v_cvt_pk_bf16_f32 v192, v78, v79
	v_cvt_pk_bf16_f32 v193, v80, v81
	v_cvt_pk_bf16_f32 v194, v82, v83
	v_cvt_pk_bf16_f32 v195, v84, v85
	global_store_dwordx4 v[168:169], v[192:195], off offset:256
	s_cmp_lg_u32 s44, 0
	s_cbranch_scc0 .Lz_rw_nokv3
	v_add_u32_e32 v165, 0x18000, v164
	global_store_dwordx4 v165, v[86:89], s[96:97]
	global_store_dwordx4 v165, v[90:93], s[96:97] offset:16
	global_store_dwordx4 v165, v[78:81], s[96:97] offset:512
	global_store_dwordx4 v165, v[82:85], s[96:97] offset:528
.Lz_rw_nokv3:
	s_movk_i32 s98, 0xa0
	v_mad_u32_u24 v8, v171, s98, v170
	global_load_dwordx4 v[86:89], v8, s[34:35]
	global_load_dwordx4 v[90:93], v8, s[34:35] offset:16
	global_load_dwordx4 v[78:81], v8, s[34:35] offset:32
	global_load_dwordx4 v[82:85], v8, s[34:35] offset:48
	s_mov_b32 vcc_lo, 0x210000
	s_mov_b32 vcc_hi, 0
	v_lshl_add_u64 v[168:169], v[166:167], 0, vcc
	s_waitcnt vmcnt(12)
	v_permlane16_swap_b32_e32 v70, v62
	v_permlane16_swap_b32_e32 v71, v63
	v_permlane16_swap_b32_e32 v72, v64
	v_permlane16_swap_b32_e32 v73, v65
	v_permlane16_swap_b32_e32 v74, v66
	v_permlane16_swap_b32_e32 v75, v67
	v_permlane16_swap_b32_e32 v76, v68
	v_permlane16_swap_b32_e32 v77, v69
	v_mul_f32_e32 v188, v62, v119
	v_mul_f32_e32 v119, v70, v119
	v_mul_f32_e32 v189, v63, v121
	v_mul_f32_e32 v121, v71, v121
	v_mul_f32_e32 v190, v64, v123
	v_mul_f32_e32 v123, v72, v123
	v_mul_f32_e32 v191, v65, v125
	v_mul_f32_e32 v125, v73, v125
	v_mul_f32_e32 v192, v66, v111
	v_mul_f32_e32 v111, v74, v111
	v_mul_f32_e32 v193, v67, v113
	v_mul_f32_e32 v113, v75, v113
	v_mul_f32_e32 v194, v68, v115
	v_mul_f32_e32 v115, v76, v115
	v_mul_f32_e32 v195, v69, v117
	v_mul_f32_e32 v117, v77, v117
	v_fma_f32 v70, v70, v118, -v188
	v_fma_f32 v62, v62, v118, v119
	v_fma_f32 v71, v71, v120, -v189
	v_fma_f32 v63, v63, v120, v121
	v_fma_f32 v72, v72, v122, -v190
	v_fma_f32 v64, v64, v122, v123
	v_fma_f32 v73, v73, v124, -v191
	v_fma_f32 v65, v65, v124, v125
	v_fma_f32 v74, v74, v110, -v192
	v_fma_f32 v66, v66, v110, v111
	v_fma_f32 v75, v75, v112, -v193
	v_fma_f32 v67, v67, v112, v113
	v_fma_f32 v76, v76, v114, -v194
	v_fma_f32 v68, v68, v114, v115
	v_fma_f32 v77, v77, v116, -v195
	v_fma_f32 v69, v69, v116, v117
	v_permlane16_swap_b32_e32 v70, v62
	v_permlane16_swap_b32_e32 v71, v63
	v_permlane16_swap_b32_e32 v72, v64
	v_permlane16_swap_b32_e32 v73, v65
	v_permlane16_swap_b32_e32 v74, v66
	v_permlane16_swap_b32_e32 v75, v67
	v_permlane16_swap_b32_e32 v76, v68
	v_permlane16_swap_b32_e32 v77, v69
	s_cmp_lt_u32 s48, 3
	s_cbranch_scc0 .Lz_rw_noqs4
	v_mul_f32_e32 v70, s8, v70
	v_mul_f32_e32 v71, s8, v71
	v_mul_f32_e32 v72, s8, v72
	v_mul_f32_e32 v73, s8, v73
	v_mul_f32_e32 v74, s8, v74
	v_mul_f32_e32 v75, s8, v75
	v_mul_f32_e32 v76, s8, v76
	v_mul_f32_e32 v77, s8, v77
	v_mul_f32_e32 v62, s8, v62
	v_mul_f32_e32 v63, s8, v63
	v_mul_f32_e32 v64, s8, v64
	v_mul_f32_e32 v65, s8, v65
	v_mul_f32_e32 v66, s8, v66
	v_mul_f32_e32 v67, s8, v67
	v_mul_f32_e32 v68, s8, v68
	v_mul_f32_e32 v69, s8, v69
.Lz_rw_noqs4:
	v_cvt_pk_bf16_f32 v188, v70, v71
	v_cvt_pk_bf16_f32 v189, v72, v73
	v_cvt_pk_bf16_f32 v190, v74, v75
	v_cvt_pk_bf16_f32 v191, v76, v77
	global_store_dwordx4 v[168:169], v[188:191], off
	v_cvt_pk_bf16_f32 v192, v62, v63
	v_cvt_pk_bf16_f32 v193, v64, v65
	v_cvt_pk_bf16_f32 v194, v66, v67
	v_cvt_pk_bf16_f32 v195, v68, v69
	global_store_dwordx4 v[168:169], v[192:195], off offset:256
	s_cmp_lg_u32 s45, 0
	s_cbranch_scc0 .Lz_rw_nokv4
	v_add_u32_e32 v165, 0x40000, v164
	global_store_dwordx4 v165, v[70:73], s[96:97]
	global_store_dwordx4 v165, v[74:77], s[96:97] offset:16
	global_store_dwordx4 v165, v[62:65], s[96:97] offset:512
	global_store_dwordx4 v165, v[66:69], s[96:97] offset:528
.Lz_rw_nokv4:
	s_movk_i32 s98, 0xb0
	v_mad_u32_u24 v9, v171, s98, v170
	global_load_dwordx4 v[70:73], v9, s[34:35]
	global_load_dwordx4 v[74:77], v9, s[34:35] offset:16
	global_load_dwordx4 v[62:65], v9, s[34:35] offset:32
	global_load_dwordx4 v[66:69], v9, s[34:35] offset:48
	s_mov_b32 vcc_lo, 0x252000
	s_mov_b32 vcc_hi, 0
	v_lshl_add_u64 v[168:169], v[166:167], 0, vcc
	s_waitcnt vmcnt(12)
	v_permlane16_swap_b32_e32 v54, v42
	v_permlane16_swap_b32_e32 v55, v43
	v_permlane16_swap_b32_e32 v56, v44
	v_permlane16_swap_b32_e32 v57, v45
	v_permlane16_swap_b32_e32 v58, v46
	v_permlane16_swap_b32_e32 v59, v47
	v_permlane16_swap_b32_e32 v60, v48
	v_permlane16_swap_b32_e32 v61, v49
	v_mul_f32_e32 v188, v42, v107
	v_mul_f32_e32 v107, v54, v107
	v_mul_f32_e32 v189, v43, v109
	v_mul_f32_e32 v109, v55, v109
	v_mul_f32_e32 v190, v44, v103
	v_mul_f32_e32 v103, v56, v103
	v_mul_f32_e32 v191, v45, v105
	v_mul_f32_e32 v105, v57, v105
	v_mul_f32_e32 v192, v46, v99
	v_mul_f32_e32 v99, v58, v99
	v_mul_f32_e32 v193, v47, v101
	v_mul_f32_e32 v101, v59, v101
	v_mul_f32_e32 v194, v48, v95
	v_mul_f32_e32 v95, v60, v95
	v_mul_f32_e32 v195, v49, v97
	v_mul_f32_e32 v97, v61, v97
	v_fma_f32 v54, v54, v106, -v188
	v_fma_f32 v42, v42, v106, v107
	v_fma_f32 v55, v55, v108, -v189
	v_fma_f32 v43, v43, v108, v109
	v_fma_f32 v56, v56, v102, -v190
	v_fma_f32 v44, v44, v102, v103
	v_fma_f32 v57, v57, v104, -v191
	v_fma_f32 v45, v45, v104, v105
	v_fma_f32 v58, v58, v98, -v192
	v_fma_f32 v46, v46, v98, v99
	v_fma_f32 v59, v59, v100, -v193
	v_fma_f32 v47, v47, v100, v101
	v_fma_f32 v60, v60, v94, -v194
	v_fma_f32 v48, v48, v94, v95
	v_fma_f32 v61, v61, v96, -v195
	v_fma_f32 v49, v49, v96, v97
	v_permlane16_swap_b32_e32 v54, v42
	v_permlane16_swap_b32_e32 v55, v43
	v_permlane16_swap_b32_e32 v56, v44
	v_permlane16_swap_b32_e32 v57, v45
	v_permlane16_swap_b32_e32 v58, v46
	v_permlane16_swap_b32_e32 v59, v47
	v_permlane16_swap_b32_e32 v60, v48
	v_permlane16_swap_b32_e32 v61, v49
	s_cmp_lt_u32 s48, 3
	s_cbranch_scc0 .Lz_rw_noqs5
	v_mul_f32_e32 v54, s8, v54
	v_mul_f32_e32 v55, s8, v55
	v_mul_f32_e32 v56, s8, v56
	v_mul_f32_e32 v57, s8, v57
	v_mul_f32_e32 v58, s8, v58
	v_mul_f32_e32 v59, s8, v59
	v_mul_f32_e32 v60, s8, v60
	v_mul_f32_e32 v61, s8, v61
	v_mul_f32_e32 v42, s8, v42
	v_mul_f32_e32 v43, s8, v43
	v_mul_f32_e32 v44, s8, v44
	v_mul_f32_e32 v45, s8, v45
	v_mul_f32_e32 v46, s8, v46
	v_mul_f32_e32 v47, s8, v47
	v_mul_f32_e32 v48, s8, v48
	v_mul_f32_e32 v49, s8, v49
; __device__ __forceinline__ unsigned cvt_pk_bf16(float lo, float hi) { unsigned r; asm volatile("v_cvt_pk_bf16_f32 %0, %1, %2" : "=v"(r) : "v"(lo), "v"(hi)); return r; }
;     __device__ __forceinline__ void operator()(const f32x4 (&acc)[2][2][4][2], const Unit& u, int wr, int wc, int fr, int fq) const {
;     ...
;                 if (do_rope) {
;                     const f32x4* cs = (const f32x4*)(rope + (size_t)(isP ? t : 4096) * 16);
; #pragma unroll
;                     for (int q = 0; q < 4; ++q) { const f32x4 c = cs[q]; cosv[2 * q] = c[0]; sinv[2 * q] = c[1]; cosv[2 * q + 1] = c[2]; sinv[2 * q + 1] = c[3]; }
;                 }
; #pragma unroll
;                 for (int bj = 0; bj < 2; ++bj) {
;                     f32x4 v0 = acc[ai][bj][m][0], v1 = acc[ai][bj][m][1];
;                     const int cit = bj * HALF + wc * 32 + fq * 8;
;                     if (do_rope) {
; #pragma unroll
;                         for (int j = 0; j < 4; ++j) {
;                             const float p0 = __shfl_xor(v0[j], 16), p1 = __shfl_xor(v1[j], 16);
;                             const float r0 = v0[j] * cosv[j] + sgn * p0 * sinv[j], r1 = v1[j] * cosv[4 + j] + sgn * p1 * sinv[4 + j];
;                             v0[j] = fq < 2 ? r0 : v0[j]; v1[j] = fq < 2 ? r1 : v1[j];
;                         }
;                     }
;                     if (pn < 3) { v0 = v0 * QSCALE; v1 = v1 * QSCALE; }
;                     u32x4 w; w.x = cvt_pk_bf16(v0[0], v0[1]); w.y = cvt_pk_bf16(v0[2], v0[3]); w.z = cvt_pk_bf16(v1[0], v1[1]); w.w = cvt_pk_bf16(v1[2], v1[3]);
;                     *(u32x4*)(Z + (size_t)row * NZ + pn * BM + cit) = w;
;                     if (is_kv) {
;                         float* dst = nullptr;
;                         if (isP && t >= 4096 - W) dst = out + okp + ((size_t)(b * W + t - (4096 - W)) * 2 + kvsel) * 256 + cit;
;                         else if (isS) dst = out + oks + ((size_t)(b * W + W - 1) * 2 + kvsel) * 256 + cit;
;                         if (dst) { *(f32x4*)dst = v0; *(f32x4*)(dst + 4) = v1; }
.Lz_rw_noqs5:
	v_cvt_pk_bf16_f32 v188, v54, v55
	v_cvt_pk_bf16_f32 v189, v56, v57
	v_cvt_pk_bf16_f32 v190, v58, v59
	v_cvt_pk_bf16_f32 v191, v60, v61
	global_store_dwordx4 v[168:169], v[188:191], off
	v_cvt_pk_bf16_f32 v192, v42, v43
	v_cvt_pk_bf16_f32 v193, v44, v45
	v_cvt_pk_bf16_f32 v194, v46, v47
	v_cvt_pk_bf16_f32 v195, v48, v49
	global_store_dwordx4 v[168:169], v[192:195], off offset:256
	s_cmp_lg_u32 s45, 0
	s_cbranch_scc0 .Lz_rw_nokv5
	v_add_u32_e32 v165, 0x48000, v164
	global_store_dwordx4 v165, v[54:57], s[96:97]
	global_store_dwordx4 v165, v[58:61], s[96:97] offset:16
	global_store_dwordx4 v165, v[42:45], s[96:97] offset:512
	global_store_dwordx4 v165, v[46:49], s[96:97] offset:528
.Lz_rw_nokv5:
	s_mov_b32 vcc_lo, 0x294000
	s_mov_b32 vcc_hi, 0
	v_lshl_add_u64 v[168:169], v[166:167], 0, vcc
	s_waitcnt vmcnt(8)
	v_permlane16_swap_b32_e32 v38, v30
	v_permlane16_swap_b32_e32 v39, v31
	v_permlane16_swap_b32_e32 v40, v32
	v_permlane16_swap_b32_e32 v41, v33
	v_permlane16_swap_b32_e32 v34, v26
	v_permlane16_swap_b32_e32 v35, v27
	v_permlane16_swap_b32_e32 v36, v28
	v_permlane16_swap_b32_e32 v37, v29
	v_mul_f32_e32 v188, v30, v87
	v_mul_f32_e32 v87, v38, v87
	v_mul_f32_e32 v189, v31, v89
	v_mul_f32_e32 v89, v39, v89
	v_mul_f32_e32 v190, v32, v91
	v_mul_f32_e32 v91, v40, v91
	v_mul_f32_e32 v191, v33, v93
	v_mul_f32_e32 v93, v41, v93
	v_mul_f32_e32 v192, v26, v79
	v_mul_f32_e32 v79, v34, v79
	v_mul_f32_e32 v193, v27, v81
	v_mul_f32_e32 v81, v35, v81
	v_mul_f32_e32 v194, v28, v83
	v_mul_f32_e32 v83, v36, v83
	v_mul_f32_e32 v195, v29, v85
	v_mul_f32_e32 v85, v37, v85
	v_fma_f32 v38, v38, v86, -v188
	v_fma_f32 v30, v30, v86, v87
	v_fma_f32 v39, v39, v88, -v189
	v_fma_f32 v31, v31, v88, v89
	v_fma_f32 v40, v40, v90, -v190
	v_fma_f32 v32, v32, v90, v91
	v_fma_f32 v41, v41, v92, -v191
	v_fma_f32 v33, v33, v92, v93
	v_fma_f32 v34, v34, v78, -v192
	v_fma_f32 v26, v26, v78, v79
	v_fma_f32 v35, v35, v80, -v193
	v_fma_f32 v27, v27, v80, v81
	v_fma_f32 v36, v36, v82, -v194
	v_fma_f32 v28, v28, v82, v83
	v_fma_f32 v37, v37, v84, -v195
	v_fma_f32 v29, v29, v84, v85
	v_permlane16_swap_b32_e32 v38, v30
	v_permlane16_swap_b32_e32 v39, v31
	v_permlane16_swap_b32_e32 v40, v32
	v_permlane16_swap_b32_e32 v41, v33
	v_permlane16_swap_b32_e32 v34, v26
	v_permlane16_swap_b32_e32 v35, v27
	v_permlane16_swap_b32_e32 v36, v28
	v_permlane16_swap_b32_e32 v37, v29
	s_cmp_lt_u32 s48, 3
	s_cbranch_scc0 .Lz_rw_noqs6
	v_mul_f32_e32 v38, s8, v38
	v_mul_f32_e32 v39, s8, v39
	v_mul_f32_e32 v40, s8, v40
	v_mul_f32_e32 v41, s8, v41
	v_mul_f32_e32 v34, s8, v34
	v_mul_f32_e32 v35, s8, v35
	v_mul_f32_e32 v36, s8, v36
	v_mul_f32_e32 v37, s8, v37
	v_mul_f32_e32 v30, s8, v30
	v_mul_f32_e32 v31, s8, v31
	v_mul_f32_e32 v32, s8, v32
	v_mul_f32_e32 v33, s8, v33
	v_mul_f32_e32 v26, s8, v26
	v_mul_f32_e32 v27, s8, v27
	v_mul_f32_e32 v28, s8, v28
	v_mul_f32_e32 v29, s8, v29
.Lz_rw_noqs6:
	v_cvt_pk_bf16_f32 v188, v38, v39
	v_cvt_pk_bf16_f32 v189, v40, v41
	v_cvt_pk_bf16_f32 v190, v34, v35
	v_cvt_pk_bf16_f32 v191, v36, v37
	global_store_dwordx4 v[168:169], v[188:191], off
	v_cvt_pk_bf16_f32 v192, v30, v31
	v_cvt_pk_bf16_f32 v193, v32, v33
	v_cvt_pk_bf16_f32 v194, v26, v27
	v_cvt_pk_bf16_f32 v195, v28, v29
	global_store_dwordx4 v[168:169], v[192:195], off offset:256
	s_cmp_lg_u32 s45, 0
	s_cbranch_scc0 .Lz_rw_nokv6
	v_add_u32_e32 v165, 0x50000, v164
	global_store_dwordx4 v165, v[38:41], s[96:97]
	global_store_dwordx4 v165, v[34:37], s[96:97] offset:16
	global_store_dwordx4 v165, v[30:33], s[96:97] offset:512
	global_store_dwordx4 v165, v[26:29], s[96:97] offset:528
.Lz_rw_nokv6:
	s_mov_b32 vcc_lo, 0x2d6000
	s_mov_b32 vcc_hi, 0
	v_lshl_add_u64 v[168:169], v[166:167], 0, vcc
	s_waitcnt vmcnt(4)
	v_permlane16_swap_b32_e32 v18, v14
	v_permlane16_swap_b32_e32 v19, v15
	v_permlane16_swap_b32_e32 v20, v16
	v_permlane16_swap_b32_e32 v21, v17
	v_permlane16_swap_b32_e32 v22, v10
	v_permlane16_swap_b32_e32 v23, v11
	v_permlane16_swap_b32_e32 v24, v12
	v_permlane16_swap_b32_e32 v25, v13
	v_mul_f32_e32 v188, v14, v71
	v_mul_f32_e32 v71, v18, v71
	v_mul_f32_e32 v189, v15, v73
	v_mul_f32_e32 v73, v19, v73
	v_mul_f32_e32 v190, v16, v75
	v_mul_f32_e32 v75, v20, v75
	v_mul_f32_e32 v191, v17, v77
	v_mul_f32_e32 v77, v21, v77
	v_mul_f32_e32 v192, v10, v63
	v_mul_f32_e32 v63, v22, v63
	v_mul_f32_e32 v193, v11, v65
	v_mul_f32_e32 v65, v23, v65
	v_mul_f32_e32 v194, v12, v67
	v_mul_f32_e32 v67, v24, v67
	v_mul_f32_e32 v195, v13, v69
	v_mul_f32_e32 v69, v25, v69
	v_fma_f32 v18, v18, v70, -v188
	v_fma_f32 v14, v14, v70, v71
	v_fma_f32 v19, v19, v72, -v189
	v_fma_f32 v15, v15, v72, v73
	v_fma_f32 v20, v20, v74, -v190
	v_fma_f32 v16, v16, v74, v75
	v_fma_f32 v21, v21, v76, -v191
	v_fma_f32 v17, v17, v76, v77
	v_fma_f32 v22, v22, v62, -v192
	v_fma_f32 v10, v10, v62, v63
	v_fma_f32 v23, v23, v64, -v193
	v_fma_f32 v11, v11, v64, v65
	v_fma_f32 v24, v24, v66, -v194
	v_fma_f32 v12, v12, v66, v67
	v_fma_f32 v25, v25, v68, -v195
	v_fma_f32 v13, v13, v68, v69
	v_permlane16_swap_b32_e32 v18, v14
	v_permlane16_swap_b32_e32 v19, v15
	v_permlane16_swap_b32_e32 v20, v16
	v_permlane16_swap_b32_e32 v21, v17
	v_permlane16_swap_b32_e32 v22, v10
	v_permlane16_swap_b32_e32 v23, v11
	v_permlane16_swap_b32_e32 v24, v12
	v_permlane16_swap_b32_e32 v25, v13
	s_cmp_lt_u32 s48, 3
	s_cbranch_scc0 .Lz_rw_noqs7
	v_mul_f32_e32 v18, s8, v18
	v_mul_f32_e32 v19, s8, v19
	v_mul_f32_e32 v20, s8, v20
	v_mul_f32_e32 v21, s8, v21
	v_mul_f32_e32 v22, s8, v22
	v_mul_f32_e32 v23, s8, v23
	v_mul_f32_e32 v24, s8, v24
	v_mul_f32_e32 v25, s8, v25
	v_mul_f32_e32 v14, s8, v14
	v_mul_f32_e32 v15, s8, v15
	v_mul_f32_e32 v16, s8, v16
	v_mul_f32_e32 v17, s8, v17
	v_mul_f32_e32 v10, s8, v10
	v_mul_f32_e32 v11, s8, v11
	v_mul_f32_e32 v12, s8, v12
	v_mul_f32_e32 v13, s8, v13
.Lz_rw_noqs7:
	v_cvt_pk_bf16_f32 v188, v18, v19
	v_cvt_pk_bf16_f32 v189, v20, v21
	v_cvt_pk_bf16_f32 v190, v22, v23
	v_cvt_pk_bf16_f32 v191, v24, v25
	global_store_dwordx4 v[168:169], v[188:191], off
	v_cvt_pk_bf16_f32 v192, v14, v15
	v_cvt_pk_bf16_f32 v193, v16, v17
	v_cvt_pk_bf16_f32 v194, v10, v11
	v_cvt_pk_bf16_f32 v195, v12, v13
	global_store_dwordx4 v[168:169], v[192:195], off offset:256
	s_cmp_lg_u32 s45, 0
	s_cbranch_scc0 .Lz_rw_nokv7
	v_add_u32_e32 v165, 0x58000, v164
	global_store_dwordx4 v165, v[18:21], s[96:97]
	global_store_dwordx4 v165, v[22:25], s[96:97] offset:16
	global_store_dwordx4 v165, v[14:17], s[96:97] offset:512
	global_store_dwordx4 v165, v[10:13], s[96:97] offset:528
